# snake MFMA order; static s_setprio 1 for waves 0-3 per GEMM phase instead of per-block flips
# speedup vs baseline: 1.0138x; 1.0102x over previous
.LBB0_127:
	s_or_b64 exec, exec, s[34:35]
	s_cmp_lt_i32 s58, 2
	s_cselect_b64 s[0:1], -1, 0
	s_add_i32 s2, 0, 0x23fcc
	v_mov_b32_e32 v0, s2
	s_waitcnt lgkmcnt(0)
	s_barrier
	ds_read_b32 v0, v0
	s_and_b64 s[6:7], s[0:1], s[30:31]
	s_andn2_b64 vcc, exec, s[6:7]
	s_waitcnt lgkmcnt(0)
	v_readfirstlane_b32 s84, v0
	s_cbranch_vccnz .LBB0_149
	v_readfirstlane_b32 s3, v220
	s_movk_i32 s0, 0x800
	s_cmpk_gt_i32 s84, 0xaff
	s_cbranch_scc1 .LBB0_149
	v_lshrrev_b32_e32 v0, 5, v220
	v_lshrrev_b32_e32 v2, 1, v220
	v_and_b32_e32 v0, 4, v0
	v_bfe_u32 v1, v220, 2, 2
	v_and_b32_e32 v17, 24, v2
	v_or3_b32 v0, v0, v1, v17
	v_lshlrev_b32_e32 v1, 4, v220
	v_add_u32_e32 v2, 0x2000, v1
	v_lshrrev_b32_e32 v2, 7, v2
	v_and_b32_e32 v4, 32, v220
	s_add_u32 s24, s56, 0x8200000
	s_movk_i32 s2, 0xe0
	v_bitop3_b32 v12, v1, v4, 48 bitop3:0x6c
	v_and_b32_e32 v13, 64, v220
	v_and_b32_e32 v14, 0xf0, v2
	v_bfe_u32 v15, v220, 2, 4
	s_addc_u32 s25, s57, 0
	v_and_or_b32 v3, v2, s2, v0
	v_or_b32_e32 v1, v12, v13
	v_or_b32_e32 v2, v14, v15
	s_add_u32 s26, s56, 0x100000
	v_lshrrev_b32_e32 v1, 1, v1
	v_mul_lo_u32 v2, s0, v2
	s_addc_u32 s27, s57, 0
	v_add_lshl_u32 v130, v2, v1, 1
	v_lshrrev_b32_e32 v2, 3, v220
	s_movk_i32 s2, 0x60
	s_ashr_i32 s29, s84, 31
	v_and_or_b32 v0, v2, s2, v0
	s_lshr_b32 s2, s29, 29
	s_add_i32 s2, s84, s2
	s_lshr_b32 s4, s3, 6
	s_ashr_i32 s1, s0, 31
	s_ashr_i32 s12, s2, 3
	s_and_b32 s2, s2, -8
	s_lshr_b32 s5, s3, 8
	s_lshl_b64 s[8:9], s[0:1], 9
	s_lshl_b64 s[10:11], s[0:1], 8
	s_lshl_b32 s28, s4, 10
	s_sub_i32 s2, s84, s2
	s_cmp_lt_i32 s2, 0
	s_movk_i32 s30, 0x161
	s_cselect_b32 s13, s30, 0x160
	s_mul_i32 s2, s2, s13
	s_add_i32 s2, s2, s12
	s_mul_hi_i32 s12, s2, 0x2e8ba2e9
	s_lshr_b32 s13, s12, 31
	s_ashr_i32 s12, s12, 6
	s_add_i32 s12, s12, s13
	s_lshl_b32 s13, s12, 3
	s_mulk_i32 s12, 0x160
	s_sub_i32 s12, s2, s12
	s_bfe_u32 s2, s12, 0x3001c
	s_add_i32 s14, s12, s2
	s_sext_i32_i16 s16, s14
	s_and_b32 s14, s14, 0xfff8
	s_sub_i32 s12, s12, s14
	s_sext_i32_i16 s12, s12
	s_add_i32 s50, s13, s12
	s_ashr_i32 s12, s50, 31
	s_mul_i32 s12, s8, s12
	s_mul_hi_u32 s13, s8, s50
	s_add_i32 s14, s13, s12
	s_lshr_b64 s[12:13], s[0:1], 23
	s_lshr_b32 s2, s16, 3
	s_mul_i32 s13, s12, s50
	s_add_i32 s17, s14, s13
	s_bfe_i64 s[14:15], s[2:3], 0x100000
	s_ashr_i32 s13, s16, 3
	s_mul_hi_u32 s14, s8, s13
	s_mul_i32 s15, s8, s15
	s_add_i32 s14, s14, s15
	s_mul_i32 s12, s12, s13
	s_add_i32 s14, s14, s12
	s_mul_i32 s12, s8, s13
	s_add_u32 s22, s26, s12
	v_mul_lo_u32 v0, s0, v0
	s_addc_u32 s23, s27, s14
	s_add_i32 s31, s28, 0
	v_add_lshl_u32 v132, v0, v1, 1
	s_add_i32 m0, s31, 0x10000
	v_mul_lo_u32 v3, s0, v3
	global_load_lds_dwordx4 v132, s[22:23]
	s_add_i32 m0, s31, 0x12000
	v_add_lshl_u32 v128, v3, v1, 1
	s_add_u32 s12, s22, s10
	global_load_lds_dwordx4 v128, s[22:23]
	s_addc_u32 s13, s23, s11
	s_add_i32 m0, s31, 0x14000
	v_and_b32_e32 v16, 0x70, v2
	s_mul_i32 s18, s8, s50
	global_load_lds_dwordx4 v132, s[12:13]
	s_add_i32 m0, s31, 0x16000
	v_or_b32_e32 v0, v16, v15
	s_add_u32 s20, s24, s18
	v_mul_lo_u32 v0, s0, v0
	s_addc_u32 s21, s25, s17
	s_add_i32 s33, s31, 0x2000
	v_add_lshl_u32 v134, v0, v1, 1
	global_load_lds_dwordx4 v128, s[12:13]
	s_mov_b32 m0, s31
	s_add_u32 s14, s20, s10
	global_load_lds_dwordx4 v134, s[20:21]
	s_mov_b32 m0, s33
	s_addc_u32 s15, s21, s11
	s_add_i32 s34, s31, 0x4000
	global_load_lds_dwordx4 v130, s[20:21]
	s_mov_b32 m0, s34
	s_add_i32 s35, s31, 0x6000
	global_load_lds_dwordx4 v134, s[14:15]
	s_mov_b32 m0, s35
	v_mov_b32_e32 v137, 0
	global_load_lds_dwordx4 v130, s[14:15]
	v_mov_b32_e32 v133, v137
	v_mov_b32_e32 v129, v137
	v_mov_b32_e32 v135, v137
	v_mov_b32_e32 v131, v137
	s_cmp_eq_u32 s5, 1
	s_mov_b32 s36, 0
	v_lshl_add_u64 v[8:9], s[22:23], 0, v[132:133]
	v_lshl_add_u64 v[4:5], s[22:23], 0, v[128:129]
	v_lshl_add_u64 v[2:3], s[12:13], 0, v[132:133]
	v_lshl_add_u64 v[0:1], s[12:13], 0, v[128:129]
	v_lshl_add_u64 v[6:7], s[20:21], 0, v[134:135]
	s_cselect_b64 s[12:13], -1, 0
	s_cmp_lg_u32 s5, 1
	v_lshl_add_u64 v[10:11], s[20:21], 0, v[130:131]
	s_setprio 1
	s_cbranch_scc1 .LBB0_131
	s_setprio 0
	s_barrier

.LBB0_210:
	s_andn2_b64 vcc, exec, s[4:5]
	s_cbranch_vccnz .LBB0_252
	s_add_u32 s33, s56, 0xc200000
	s_addc_u32 s34, s57, 0
	s_add_u32 s35, s56, 0x2d00000
	s_addc_u32 s36, s57, 0
	s_ashr_i32 s1, s0, 31
	s_lshl_b64 s[8:9], s[0:1], 9
	s_ashr_i32 s6, s54, 31
	s_mul_i32 s6, s8, s6
	s_mul_hi_u32 s7, s8, s54
	s_add_i32 s10, s7, s6
	s_lshr_b64 s[6:7], s[0:1], 23
	s_mul_i32 s7, s6, s54
	s_add_i32 s10, s10, s7
	s_ashr_i32 s7, s55, 31
	s_mul_i32 s7, s8, s7
	s_mul_hi_u32 s12, s8, s55
	s_lshr_b32 s5, s18, 6
	s_add_i32 s7, s12, s7
	s_mul_i32 s6, s6, s55
	s_lshr_b32 s4, s18, 8
	v_lshlrev_b32_e32 v3, 4, v220
	v_and_b32_e32 v0, 32, v220
	v_lshlrev_b32_e32 v2, 5, v220
	s_lshl_b32 s37, s5, 10
	s_add_i32 s7, s7, s6
	s_mul_i32 s6, s8, s55
	v_bitop3_b32 v0, v3, v0, 48 bitop3:0x6c
	v_and_b32_e32 v1, 64, v220
	v_and_b32_e32 v2, 0x780, v2
	s_add_u32 s26, s35, s6
	v_or3_b32 v5, v2, v1, v0
	v_and_b32_e32 v4, 0x3800, v3
	s_addc_u32 s27, s36, s7
	s_add_i32 s38, s37, 0
	v_or_b32_e32 v128, v5, v4
	v_add_u32_e32 v3, 0x2000, v3
	s_add_i32 m0, s38, 0x10000
	v_and_b32_e32 v3, 0x7800, v3
	global_load_lds_dwordx4 v128, s[26:27]
	s_add_i32 m0, s38, 0x12000
	v_or_b32_e32 v130, v5, v3
	s_add_u32 s6, s26, 0x4000
	global_load_lds_dwordx4 v130, s[26:27]
	s_addc_u32 s7, s27, 0
	s_add_i32 m0, s38, 0x14000
	s_mul_i32 s11, s8, s54
	global_load_lds_dwordx4 v128, s[6:7]
	s_add_i32 m0, s38, 0x16000
	s_add_u32 s24, s33, s11
	s_addc_u32 s25, s34, s10
	s_add_i32 s39, s38, 0x2000
	global_load_lds_dwordx4 v130, s[6:7]
	s_mov_b32 m0, s38
	s_add_u32 s6, s24, 0x4000
	global_load_lds_dwordx4 v128, s[24:25]
	s_mov_b32 m0, s39
	s_addc_u32 s7, s25, 0
	s_add_i32 s40, s38, 0x4000
	global_load_lds_dwordx4 v130, s[24:25]
	s_mov_b32 m0, s40
	s_add_i32 s41, s38, 0x6000
	global_load_lds_dwordx4 v128, s[6:7]
	s_mov_b32 m0, s41
	v_mov_b32_e32 v129, 0
	global_load_lds_dwordx4 v130, s[6:7]
	s_cmp_eq_u32 s4, 1
	s_mov_b32 s42, 0
	s_cselect_b64 s[10:11], -1, 0
	s_cmp_lg_u32 s4, 1
	v_mov_b32_e32 v131, v129
	s_setprio 1
	s_cbranch_scc1 .LBB0_213
	s_setprio 0
	s_barrier

.LBB0_309:
	s_andn2_b64 vcc, exec, s[4:5]
	s_cbranch_vccnz .LBB0_434
	v_writelane_b32 v252, s2, 48
	v_lshrrev_b32_e32 v2, 1, v220
	v_lshrrev_b32_e32 v3, 5, v220
	v_writelane_b32 v252, s3, 49
	v_writelane_b32 v252, s78, 50
	v_writelane_b32 v252, s80, 51
	v_writelane_b32 v252, s88, 52
	s_add_u32 s66, s56, 0x8200000
	v_lshlrev_b32_e32 v0, 4, v220
	v_writelane_b32 v252, s89, 53
	v_writelane_b32 v252, s76, 54
	s_waitcnt lgkmcnt(0)
	v_and_b32_e32 v1, 32, v220
	v_and_b32_e32 v2, 24, v2
	v_writelane_b32 v252, s77, 55
	v_writelane_b32 v252, s85, 56
	v_and_b32_e32 v3, 4, v3
	v_bfe_u32 v4, v220, 2, 2
	v_readlane_b32 s68, v252, 16
	s_addc_u32 s67, s57, 0
	v_bitop3_b32 v12, v0, v1, 48 bitop3:0x6c
	v_or3_b32 v2, v3, v4, v2
	v_lshrrev_b32_e32 v3, 3, v220
	s_movk_i32 s1, 0x60
	v_add_u32_e32 v0, 0x2000, v0
	v_readlane_b32 s69, v252, 17
	s_add_u32 s68, s56, 0x4300000
	v_and_b32_e32 v15, 0x70, v3
	v_and_or_b32 v3, v3, s1, v2
	v_lshrrev_b32_e32 v0, 7, v0
	s_movk_i32 s1, 0xe0
	s_addc_u32 s69, s57, 0
	v_and_b32_e32 v16, 0xf0, v0
	v_and_or_b32 v0, v0, s1, v2
	s_ashr_i32 s1, s0, 31
	s_lshr_b64 s[14:15], s[0:1], 23
	s_lshl_b64 s[8:9], s[0:1], 9
	s_ashr_i32 s7, s12, 31
	s_ashr_i32 s15, s89, 31
	s_mul_i32 s7, s8, s7
	s_mul_hi_u32 s13, s8, s12
	s_mul_i32 s15, s8, s15
	s_mul_hi_u32 s16, s8, s89
	v_readlane_b32 s70, v252, 18
	s_lshr_b32 s4, s6, 6
	s_add_i32 s7, s13, s7
	s_mul_i32 s13, s14, s12
	s_add_i32 s15, s16, s15
	s_mul_i32 s14, s14, s89
	v_and_b32_e32 v13, 64, v220
	s_lshr_b32 s5, s6, 8
	s_lshl_b64 s[10:11], s[0:1], 8
	s_lshl_b32 s70, s4, 10
	s_add_i32 s7, s7, s13
	s_add_i32 s15, s15, s14
	s_mul_i32 s14, s8, s89
	v_readlane_b32 s71, v252, 19
	v_or_b32_e32 v1, v12, v13
	s_add_u32 s50, s68, s14
	v_lshrrev_b32_e32 v1, 1, v1
	v_mul_lo_u32 v3, s0, v3
	s_addc_u32 s51, s69, s15
	s_add_i32 s71, s70, 0
	v_add_lshl_u32 v166, v3, v1, 1
	s_add_i32 m0, s71, 0x10000
	v_mul_lo_u32 v0, s0, v0
	global_load_lds_dwordx4 v166, s[50:51]
	s_add_i32 m0, s71, 0x12000
	v_add_lshl_u32 v170, v0, v1, 1
	s_add_u32 s14, s50, s10
	global_load_lds_dwordx4 v170, s[50:51]
	s_addc_u32 s15, s51, s11
	s_add_i32 m0, s71, 0x14000
	v_bfe_u32 v14, v220, 2, 4
	s_mul_i32 s13, s8, s12
	global_load_lds_dwordx4 v166, s[14:15]
	s_add_i32 m0, s71, 0x16000
	v_readlane_b32 s72, v252, 20
	v_or_b32_e32 v4, v15, v14
	s_add_u32 s52, s66, s13
	v_mul_lo_u32 v4, s0, v4
	v_or_b32_e32 v3, v16, v14
	s_addc_u32 s53, s67, s7
	s_add_i32 s72, s71, 0x2000
	v_readlane_b32 s73, v252, 21
	v_add_lshl_u32 v164, v4, v1, 1
	v_mul_lo_u32 v2, s0, v3
	global_load_lds_dwordx4 v170, s[14:15]
	s_mov_b32 m0, s71
	s_add_u32 s16, s52, s10
	v_readlane_b32 s74, v252, 22
	v_add_lshl_u32 v168, v2, v1, 1
	global_load_lds_dwordx4 v164, s[52:53]
	s_mov_b32 m0, s72
	s_addc_u32 s17, s53, s11
	s_add_i32 s73, s71, 0x4000
	global_load_lds_dwordx4 v168, s[52:53]
	s_mov_b32 m0, s73
	s_add_i32 s74, s71, 0x6000
	global_load_lds_dwordx4 v164, s[16:17]
	s_mov_b32 m0, s74
	v_mov_b32_e32 v173, 0
	global_load_lds_dwordx4 v168, s[16:17]
	v_mov_b32_e32 v167, v173
	v_mov_b32_e32 v171, v173
	v_mov_b32_e32 v165, v173
	v_mov_b32_e32 v169, v173
	s_cmp_eq_u32 s5, 1
	s_mov_b32 s13, 0
	v_lshl_add_u64 v[8:9], s[50:51], 0, v[166:167]
	v_lshl_add_u64 v[4:5], s[50:51], 0, v[170:171]
	v_lshl_add_u64 v[2:3], s[14:15], 0, v[166:167]
	v_lshl_add_u64 v[0:1], s[14:15], 0, v[170:171]
	v_lshl_add_u64 v[6:7], s[52:53], 0, v[164:165]
	s_cselect_b64 s[14:15], -1, 0
	s_cmp_lg_u32 s5, 1
	v_lshl_add_u64 v[10:11], s[52:53], 0, v[168:169]
	v_readlane_b32 s75, v252, 23
	v_readlane_b32 s76, v252, 24
	v_readlane_b32 s77, v252, 25
	v_readlane_b32 s78, v252, 26
	v_readlane_b32 s79, v252, 27
	v_readlane_b32 s80, v252, 28
	v_readlane_b32 s81, v252, 29
	v_readlane_b32 s82, v252, 30
	v_readlane_b32 s83, v252, 31
	s_setprio 1
	s_cbranch_scc1 .LBB0_312
	s_setprio 0
	s_barrier

.LBB0_575:
	s_ashr_i32 s2, s1, 3
	s_add_u32 s36, s56, 0x8200000
	s_addc_u32 s37, s57, 0
	s_add_u32 s38, s56, 0x6900000
	s_addc_u32 s39, s57, 0
	s_add_i32 s2, s10, s2
	s_ashr_i32 s10, s2, 31
	s_lshr_b32 s10, s10, 26
	s_add_i32 s10, s2, s10
	s_ashr_i32 s11, s10, 6
	s_and_b32 s10, s10, 0xffc0
	s_sub_i32 s10, s2, s10
	s_bfe_i32 s2, s10, 0x80000
	v_lshrrev_b32_e32 v2, 1, v220
	s_bfe_u32 s2, s2, 0x3000c
	v_and_b32_e32 v16, 24, v2
	v_lshrrev_b32_e32 v2, 5, v220
	s_add_i32 s12, s10, s2
	v_lshlrev_b32_e32 v0, 4, v220
	v_and_b32_e32 v1, 32, v220
	v_and_b32_e32 v2, 4, v2
	v_bfe_u32 v3, v220, 2, 2
	s_bfe_i32 s2, s12, 0x80000
	s_and_b32 s12, s12, 0xf8
	v_bitop3_b32 v13, v0, v1, 48 bitop3:0x6c
	v_or3_b32 v2, v2, v3, v16
	v_lshrrev_b32_e32 v3, 3, v220
	s_movk_i32 s1, 0x60
	v_add_u32_e32 v0, 0x2000, v0
	s_sub_i32 s10, s10, s12
	v_and_b32_e32 v17, 0x70, v3
	v_and_or_b32 v3, v3, s1, v2
	v_lshrrev_b32_e32 v0, 7, v0
	s_movk_i32 s1, 0xe0
	s_lshl_b32 s11, s11, 3
	s_sext_i32_i8 s10, s10
	v_and_b32_e32 v18, 0xf0, v0
	v_and_or_b32 v0, v0, s1, v2
	s_ashr_i32 s1, s0, 31
	s_add_i32 s60, s11, s10
	s_lshl_b64 s[6:7], s[0:1], 9
	s_ashr_i32 s10, s60, 31
	s_mul_i32 s10, s6, s10
	s_mul_hi_u32 s11, s6, s60
	s_sext_i32_i16 s14, s2
	s_add_i32 s12, s11, s10
	s_lshr_b64 s[10:11], s[0:1], 23
	s_lshr_b32 s3, s18, 8
	s_lshr_b32 s2, s14, 3
	s_mul_i32 s11, s10, s60
	s_add_i32 s15, s12, s11
	s_bfe_i64 s[12:13], s[2:3], 0x100000
	s_ashr_i32 s11, s14, 3
	s_mul_hi_u32 s12, s6, s11
	s_mul_i32 s13, s6, s13
	s_lshr_b32 s16, s18, 6
	s_add_i32 s12, s12, s13
	s_mul_i32 s10, s10, s11
	v_and_b32_e32 v14, 64, v220
	s_lshl_b64 s[8:9], s[0:1], 8
	s_lshl_b32 s40, s16, 10
	s_add_i32 s12, s12, s10
	s_mul_i32 s10, s6, s11
	v_or_b32_e32 v1, v13, v14
	s_add_u32 s34, s38, s10
	v_lshrrev_b32_e32 v1, 1, v1
	v_mul_lo_u32 v3, s0, v3
	s_addc_u32 s35, s39, s12
	s_add_i32 s41, s40, 0
	v_add_lshl_u32 v130, v3, v1, 1
	s_add_i32 m0, s41, 0x10000
	v_mul_lo_u32 v0, s0, v0
	global_load_lds_dwordx4 v130, s[34:35]
	s_add_i32 m0, s41, 0x12000
	v_add_lshl_u32 v134, v0, v1, 1
	s_add_u32 s10, s34, s8
	global_load_lds_dwordx4 v134, s[34:35]
	s_addc_u32 s11, s35, s9
	s_add_i32 m0, s41, 0x14000
	v_bfe_u32 v15, v220, 2, 4
	s_mul_i32 s17, s6, s60
	global_load_lds_dwordx4 v130, s[10:11]
	s_add_i32 m0, s41, 0x16000
	v_or_b32_e32 v4, v17, v15
	s_add_u32 s30, s36, s17
	v_mul_lo_u32 v4, s0, v4
	v_or_b32_e32 v3, v18, v15
	s_addc_u32 s31, s37, s15
	s_add_i32 s42, s41, 0x2000
	v_add_lshl_u32 v128, v4, v1, 1
	v_mul_lo_u32 v2, s0, v3
	global_load_lds_dwordx4 v134, s[10:11]
	s_mov_b32 m0, s41
	s_add_u32 s12, s30, s8
	v_add_lshl_u32 v132, v2, v1, 1
	global_load_lds_dwordx4 v128, s[30:31]
	s_mov_b32 m0, s42
	s_addc_u32 s13, s31, s9
	s_add_i32 s43, s41, 0x4000
	global_load_lds_dwordx4 v132, s[30:31]
	s_mov_b32 m0, s43
	s_add_i32 s44, s41, 0x6000
	global_load_lds_dwordx4 v128, s[12:13]
	s_mov_b32 m0, s44
	v_mov_b32_e32 v131, 0
	global_load_lds_dwordx4 v132, s[12:13]
	v_mov_b32_e32 v135, v131
	v_mov_b32_e32 v129, v131
	v_mov_b32_e32 v133, v131
	s_cmp_eq_u32 s3, 1
	s_mov_b32 s45, 0
	v_lshl_add_u64 v[8:9], s[34:35], 0, v[130:131]
	v_lshl_add_u64 v[4:5], s[34:35], 0, v[134:135]
	v_lshl_add_u64 v[2:3], s[10:11], 0, v[130:131]
	v_lshl_add_u64 v[0:1], s[10:11], 0, v[134:135]
	v_lshl_add_u64 v[6:7], s[30:31], 0, v[128:129]
	s_cselect_b64 s[10:11], -1, 0
	s_cmp_lg_u32 s3, 1
	v_lshl_add_u64 v[10:11], s[30:31], 0, v[132:133]
	s_setprio 1
	s_cbranch_scc1 .LBB0_577
	s_setprio 0
	s_barrier

.LBB0_746:
	s_ashr_i32 s2, s1, 3
	s_add_u32 s29, s56, 0xa200000
	s_addc_u32 s30, s57, 0
	s_add_u32 s31, s56, 0x6d00000
	s_addc_u32 s33, s57, 0
	s_add_i32 s2, s10, s2
	s_ashr_i32 s10, s2, 31
	s_lshr_b32 s10, s10, 26
	s_add_i32 s10, s2, s10
	s_ashr_i32 s11, s10, 6
	s_and_b32 s10, s10, 0xffc0
	s_sub_i32 s10, s2, s10
	s_bfe_i32 s2, s10, 0x80000
	v_lshrrev_b32_e32 v2, 1, v220
	s_bfe_u32 s2, s2, 0x3000c
	v_and_b32_e32 v15, 24, v2
	v_lshrrev_b32_e32 v2, 5, v220
	s_add_i32 s12, s10, s2
	v_lshlrev_b32_e32 v0, 4, v220
	v_and_b32_e32 v1, 32, v220
	v_and_b32_e32 v2, 4, v2
	v_bfe_u32 v3, v220, 2, 2
	s_bfe_i32 s2, s12, 0x80000
	s_and_b32 s12, s12, 0xf8
	v_bitop3_b32 v12, v0, v1, 48 bitop3:0x6c
	v_or3_b32 v2, v2, v3, v15
	v_lshrrev_b32_e32 v3, 3, v220
	s_movk_i32 s1, 0x60
	v_add_u32_e32 v0, 0x2000, v0
	s_sub_i32 s10, s10, s12
	v_and_b32_e32 v16, 0x70, v3
	v_and_or_b32 v3, v3, s1, v2
	v_lshrrev_b32_e32 v0, 7, v0
	s_movk_i32 s1, 0xe0
	s_lshl_b32 s11, s11, 3
	s_sext_i32_i8 s10, s10
	v_and_b32_e32 v17, 0xf0, v0
	v_and_or_b32 v0, v0, s1, v2
	s_ashr_i32 s1, s0, 31
	s_add_i32 s50, s11, s10
	s_lshl_b64 s[6:7], s[0:1], 9
	s_ashr_i32 s10, s50, 31
	s_mul_i32 s10, s6, s10
	s_mul_hi_u32 s11, s6, s50
	s_sext_i32_i16 s14, s2
	s_add_i32 s12, s11, s10
	s_lshr_b64 s[10:11], s[0:1], 23
	s_lshr_b32 s3, s20, 8
	s_lshr_b32 s2, s14, 3
	s_mul_i32 s11, s10, s50
	s_add_i32 s15, s12, s11
	s_bfe_i64 s[12:13], s[2:3], 0x100000
	s_ashr_i32 s11, s14, 3
	s_mul_hi_u32 s12, s6, s11
	s_mul_i32 s13, s6, s13
	s_lshr_b32 s18, s20, 6
	s_add_i32 s12, s12, s13
	s_mul_i32 s10, s10, s11
	v_and_b32_e32 v13, 64, v220
	s_lshl_b64 s[8:9], s[0:1], 8
	s_lshl_b32 s34, s18, 10
	s_add_i32 s12, s12, s10
	s_mul_i32 s10, s6, s11
	v_or_b32_e32 v1, v12, v13
	s_add_u32 s26, s31, s10
	v_lshrrev_b32_e32 v1, 1, v1
	v_mul_lo_u32 v3, s0, v3
	s_addc_u32 s27, s33, s12
	s_add_i32 s35, s34, 0
	v_add_lshl_u32 v154, v3, v1, 1
	s_add_i32 m0, s35, 0x10000
	v_mul_lo_u32 v0, s0, v0
	global_load_lds_dwordx4 v154, s[26:27]
	s_add_i32 m0, s35, 0x12000
	v_add_lshl_u32 v158, v0, v1, 1
	s_add_u32 s10, s26, s8
	global_load_lds_dwordx4 v158, s[26:27]
	s_addc_u32 s11, s27, s9
	s_add_i32 m0, s35, 0x14000
	v_bfe_u32 v14, v220, 2, 4
	s_mul_i32 s16, s6, s50
	global_load_lds_dwordx4 v154, s[10:11]
	s_add_i32 m0, s35, 0x16000
	v_or_b32_e32 v4, v16, v14
	s_add_u32 s24, s29, s16
	v_mul_lo_u32 v4, s0, v4
	v_or_b32_e32 v3, v17, v14
	s_addc_u32 s25, s30, s15
	s_add_i32 s36, s35, 0x2000
	v_add_lshl_u32 v152, v4, v1, 1
	v_mul_lo_u32 v2, s0, v3
	global_load_lds_dwordx4 v158, s[10:11]
	s_mov_b32 m0, s35
	s_add_u32 s12, s24, s8
	v_add_lshl_u32 v156, v2, v1, 1
	global_load_lds_dwordx4 v152, s[24:25]
	s_mov_b32 m0, s36
	s_addc_u32 s13, s25, s9
	s_add_i32 s37, s35, 0x4000
	global_load_lds_dwordx4 v156, s[24:25]
	s_mov_b32 m0, s37
	s_add_i32 s38, s35, 0x6000
	global_load_lds_dwordx4 v152, s[12:13]
	s_mov_b32 m0, s38
	v_mov_b32_e32 v155, 0
	global_load_lds_dwordx4 v156, s[12:13]
	v_mov_b32_e32 v159, v155
	v_mov_b32_e32 v153, v155
	v_mov_b32_e32 v157, v155
	s_cmp_eq_u32 s3, 1
	s_mov_b32 s39, 0
	v_lshl_add_u64 v[8:9], s[26:27], 0, v[154:155]
	v_lshl_add_u64 v[4:5], s[26:27], 0, v[158:159]
	v_lshl_add_u64 v[2:3], s[10:11], 0, v[154:155]
	v_lshl_add_u64 v[0:1], s[10:11], 0, v[158:159]
	v_lshl_add_u64 v[6:7], s[24:25], 0, v[152:153]
	s_cselect_b64 s[10:11], -1, 0
	s_cmp_lg_u32 s3, 1
	v_lshl_add_u64 v[10:11], s[24:25], 0, v[156:157]
	s_setprio 1
	s_cbranch_scc1 .LBB0_748
	s_setprio 0
	s_barrier

.LBB0_831:
	s_andn2_b64 vcc, exec, s[2:3]
	s_cbranch_vccnz .LBB0_872
	s_add_u32 s33, s56, 0x19200000
	s_addc_u32 s34, s57, 0
	s_waitcnt lgkmcnt(0)
	v_lshlrev_b32_e32 v1, 4, v220
	v_and_b32_e32 v0, 32, v220
	v_lshrrev_b32_e32 v2, 3, v220
	s_add_u32 s35, s56, 0x7100000
	v_bfe_u32 v14, v220, 2, 4
	v_bitop3_b32 v12, v1, v0, 48 bitop3:0x6c
	v_and_b32_e32 v13, 64, v220
	v_and_b32_e32 v16, 0x70, v2
	s_addc_u32 s36, s57, 0
	v_or_b32_e32 v0, v12, v13
	s_lshl_b32 s1, s0, 1
	v_or_b32_e32 v2, v16, v14
	v_mad_u64_u32 v[176:177], s[4:5], s1, v2, v[0:1]
	v_add_u32_e32 v1, 0x2000, v1
	v_lshrrev_b32_e32 v1, 7, v1
	v_and_b32_e32 v15, 0xf0, v1
	v_or_b32_e32 v1, v15, v14
	v_mad_u64_u32 v[178:179], s[4:5], s1, v1, v[0:1]
	s_ashr_i32 s1, s0, 31
	s_lshl_b64 s[8:9], s[0:1], 9
	s_ashr_i32 s4, s54, 31
	s_mul_i32 s4, s8, s4
	s_mul_hi_u32 s5, s8, s54
	s_add_i32 s12, s5, s4
	s_lshr_b64 s[4:5], s[0:1], 23
	s_mul_i32 s5, s4, s54
	s_add_i32 s12, s12, s5
	s_ashr_i32 s5, s55, 31
	s_mul_i32 s5, s8, s5
	s_mul_hi_u32 s14, s8, s55
	s_lshr_b32 s3, s22, 6
	s_add_i32 s5, s14, s5
	s_mul_i32 s4, s4, s55
	s_lshr_b32 s2, s22, 8
	s_lshl_b64 s[10:11], s[0:1], 8
	s_lshl_b32 s37, s3, 10
	s_add_i32 s5, s5, s4
	s_mul_i32 s4, s8, s55
	s_add_u32 s30, s35, s4
	s_addc_u32 s31, s36, s5
	s_add_i32 s38, s37, 0
	s_add_i32 m0, s38, 0x10000
	s_mul_i32 s13, s8, s54
	global_load_lds_dwordx4 v176, s[30:31]
	s_add_i32 m0, s38, 0x12000
	s_add_u32 s4, s30, s10
	global_load_lds_dwordx4 v178, s[30:31]
	s_addc_u32 s5, s31, s11
	s_add_i32 m0, s38, 0x14000
	v_mov_b32_e32 v177, 0
	global_load_lds_dwordx4 v176, s[4:5]
	s_add_i32 m0, s38, 0x16000
	s_add_u32 s28, s33, s13
	s_addc_u32 s29, s34, s12
	s_add_i32 s39, s38, 0x2000
	global_load_lds_dwordx4 v178, s[4:5]
	s_mov_b32 m0, s38
	s_add_u32 s12, s28, s10
	global_load_lds_dwordx4 v176, s[28:29]
	s_mov_b32 m0, s39
	s_addc_u32 s13, s29, s11
	s_add_i32 s40, s38, 0x4000
	global_load_lds_dwordx4 v178, s[28:29]
	s_mov_b32 m0, s40
	s_add_i32 s41, s38, 0x6000
	global_load_lds_dwordx4 v176, s[12:13]
	s_mov_b32 m0, s41
	v_mov_b32_e32 v179, v177
	global_load_lds_dwordx4 v178, s[12:13]
	s_cmp_eq_u32 s2, 1
	s_mov_b32 s42, 0
	v_lshl_add_u64 v[10:11], s[30:31], 0, v[176:177]
	v_lshl_add_u64 v[8:9], s[30:31], 0, v[178:179]
	v_lshl_add_u64 v[2:3], s[4:5], 0, v[176:177]
	v_lshl_add_u64 v[0:1], s[4:5], 0, v[178:179]
	v_lshl_add_u64 v[4:5], s[28:29], 0, v[176:177]
	s_cselect_b64 s[12:13], -1, 0
	s_cmp_lg_u32 s2, 1
	v_lshl_add_u64 v[6:7], s[28:29], 0, v[178:179]
	s_setprio 1
	s_cbranch_scc1 .LBB0_834
	s_setprio 0
	s_barrier

.LBB0_932:
	s_ashr_i32 s2, s1, 3
	s_add_u32 s36, s56, 0x4300000
	s_addc_u32 s37, s57, 0
	s_add_u32 s38, s56, 0x8100000
	s_addc_u32 s39, s57, 0
	s_add_i32 s2, s8, s2
	s_ashr_i32 s8, s2, 31
	s_lshr_b32 s8, s8, 26
	s_add_i32 s8, s2, s8
	s_ashr_i32 s9, s8, 6
	s_and_b32 s8, s8, 0xffc0
	s_sub_i32 s8, s2, s8
	s_bfe_i32 s2, s8, 0x80000
	s_bfe_u32 s2, s2, 0x3000c
	s_add_i32 s10, s8, s2
	s_bfe_i32 s2, s10, 0x80000
	s_and_b32 s10, s10, 0xf8
	s_sub_i32 s8, s8, s10
	s_lshl_b32 s9, s9, 3
	s_sext_i32_i8 s8, s8
	s_ashr_i32 s1, s0, 31
	s_add_i32 s62, s9, s8
	s_lshl_b64 s[4:5], s[0:1], 9
	s_ashr_i32 s8, s62, 31
	s_mul_i32 s8, s4, s8
	s_mul_hi_u32 s9, s4, s62
	s_sext_i32_i16 s12, s2
	s_add_i32 s10, s9, s8
	s_lshr_b64 s[8:9], s[0:1], 23
	s_lshr_b32 s3, s18, 8
	s_lshr_b32 s2, s12, 3
	s_mul_i32 s9, s8, s62
	s_add_i32 s13, s10, s9
	s_bfe_i64 s[10:11], s[2:3], 0x100000
	s_ashr_i32 s9, s12, 3
	s_mul_hi_u32 s10, s4, s9
	s_mul_i32 s11, s4, s11
	s_lshr_b32 s16, s18, 6
	s_add_i32 s10, s10, s11
	s_mul_i32 s8, s8, s9
	s_lshl_b64 s[6:7], s[0:1], 8
	s_lshl_b32 s40, s16, 10
	s_add_i32 s10, s10, s8
	s_mul_i32 s8, s4, s9
	v_mul_lo_u32 v0, s0, v149
	s_add_u32 s34, s38, s8
	v_add_lshl_u32 v128, v0, v148, 1
	v_mul_lo_u32 v0, s0, v150
	s_addc_u32 s35, s39, s10
	s_add_i32 s41, s40, 0
	v_add_lshl_u32 v130, v0, v148, 1
	v_mul_lo_u32 v0, s0, v151
	s_add_i32 m0, s41, 0x10000
	v_add_lshl_u32 v132, v0, v148, 1
	v_mul_lo_u32 v0, s0, v152
	global_load_lds_dwordx4 v130, s[34:35]
	s_add_i32 m0, s41, 0x12000
	v_add_lshl_u32 v134, v0, v148, 1
	s_add_u32 s8, s34, s6
	global_load_lds_dwordx4 v134, s[34:35]
	s_addc_u32 s9, s35, s7
	s_add_i32 m0, s41, 0x14000
	s_mul_i32 s17, s4, s62
	global_load_lds_dwordx4 v130, s[8:9]
	s_add_i32 m0, s41, 0x16000
	s_add_u32 s30, s36, s17
	s_addc_u32 s31, s37, s13
	s_add_i32 s42, s41, 0x2000
	global_load_lds_dwordx4 v134, s[8:9]
	s_mov_b32 m0, s41
	s_add_u32 s10, s30, s6
	global_load_lds_dwordx4 v128, s[30:31]
	s_mov_b32 m0, s42
	s_addc_u32 s11, s31, s7
	s_add_i32 s43, s41, 0x4000
	global_load_lds_dwordx4 v132, s[30:31]
	s_mov_b32 m0, s43
	s_add_i32 s44, s41, 0x6000
	global_load_lds_dwordx4 v128, s[10:11]
	s_mov_b32 m0, s44
	v_mov_b32_e32 v131, 0
	global_load_lds_dwordx4 v132, s[10:11]
	v_mov_b32_e32 v135, v131
	v_mov_b32_e32 v129, v131
	v_mov_b32_e32 v133, v131
	s_cmp_eq_u32 s3, 1
	s_mov_b32 s45, 0
	v_lshl_add_u64 v[8:9], s[34:35], 0, v[130:131]
	v_lshl_add_u64 v[4:5], s[34:35], 0, v[134:135]
	v_lshl_add_u64 v[2:3], s[8:9], 0, v[130:131]
	v_lshl_add_u64 v[0:1], s[8:9], 0, v[134:135]
	v_lshl_add_u64 v[6:7], s[30:31], 0, v[128:129]
	s_cselect_b64 s[8:9], -1, 0
	s_cmp_lg_u32 s3, 1
	v_lshl_add_u64 v[10:11], s[30:31], 0, v[132:133]
	s_setprio 1
	s_cbranch_scc1 .LBB0_934
	s_setprio 0
	s_barrier

.LBB0_956:
	v_readfirstlane_b32 s3, v220
	s_movk_i32 s0, 0x800
	s_cmpk_gt_i32 s84, 0xaff
	s_cbranch_scc1 .LBB0_977
	s_add_u32 s33, s56, 0x8200000
	s_addc_u32 s36, s57, 0
	s_add_u32 s37, s56, 0x100000
	s_addc_u32 s38, s57, 0
	s_ashr_i32 s40, s84, 31
	s_lshr_b32 s2, s40, 29
	s_add_i32 s2, s84, s2
	s_lshr_b32 s8, s3, 6
	s_ashr_i32 s1, s0, 31
	s_ashr_i32 s4, s2, 3
	s_and_b32 s2, s2, -8
	s_lshr_b32 s9, s3, 8
	s_lshl_b64 s[16:17], s[0:1], 9
	s_lshl_b64 s[18:19], s[0:1], 8
	s_lshl_b32 s39, s8, 10
	s_sub_i32 s2, s84, s2
	s_cmp_lt_i32 s2, 0
	s_movk_i32 s41, 0x161
	s_cselect_b32 s5, s41, 0x160
	s_mul_i32 s2, s2, s5
	s_add_i32 s2, s2, s4
	s_mul_hi_i32 s4, s2, 0x2e8ba2e9
	s_lshr_b32 s5, s4, 31
	s_ashr_i32 s4, s4, 6
	s_add_i32 s4, s4, s5
	s_lshl_b32 s5, s4, 3
	s_mulk_i32 s4, 0x160
	s_sub_i32 s4, s2, s4
	s_bfe_u32 s2, s4, 0x3001c
	s_add_i32 s6, s4, s2
	s_sext_i32_i16 s10, s6
	s_and_b32 s6, s6, 0xfff8
	s_sub_i32 s4, s4, s6
	s_sext_i32_i16 s4, s4
	s_add_i32 s65, s5, s4
	s_ashr_i32 s4, s65, 31
	s_mul_i32 s4, s16, s4
	s_mul_hi_u32 s5, s16, s65
	s_add_i32 s6, s5, s4
	s_lshr_b64 s[4:5], s[0:1], 23
	s_lshr_b32 s2, s10, 3
	s_mul_i32 s5, s4, s65
	s_add_i32 s12, s6, s5
	s_bfe_i64 s[6:7], s[2:3], 0x100000
	s_ashr_i32 s5, s10, 3
	s_mul_hi_u32 s6, s16, s5
	s_mul_i32 s7, s16, s7
	s_add_i32 s6, s6, s7
	s_mul_i32 s4, s4, s5
	v_mul_lo_u32 v0, s0, v152
	s_add_i32 s6, s6, s4
	s_mul_i32 s4, s16, s5
	v_add_lshl_u32 v128, v0, v148, 1
	v_mul_lo_u32 v0, s0, v151
	s_add_u32 s4, s37, s4
	v_add_lshl_u32 v130, v0, v148, 1
	v_mul_lo_u32 v0, s0, v150
	s_addc_u32 s5, s38, s6
	s_add_i32 s42, s39, 0
	v_add_lshl_u32 v132, v0, v148, 1
	s_add_i32 m0, s42, 0x10000
	s_mul_i32 s13, s16, s65
	global_load_lds_dwordx4 v132, s[4:5]
	s_add_i32 m0, s42, 0x12000
	s_add_u32 s10, s4, s18
	global_load_lds_dwordx4 v128, s[4:5]
	s_addc_u32 s11, s5, s19
	s_add_i32 m0, s42, 0x14000
	v_mul_lo_u32 v0, s0, v149
	global_load_lds_dwordx4 v132, s[10:11]
	s_add_i32 m0, s42, 0x16000
	s_add_u32 s6, s33, s13
	s_addc_u32 s7, s36, s12
	s_add_i32 s43, s42, 0x2000
	v_add_lshl_u32 v134, v0, v148, 1
	global_load_lds_dwordx4 v128, s[10:11]
	s_mov_b32 m0, s42
	s_add_u32 s12, s6, s18
	global_load_lds_dwordx4 v134, s[6:7]
	s_mov_b32 m0, s43
	s_addc_u32 s13, s7, s19
	s_add_i32 s44, s42, 0x4000
	global_load_lds_dwordx4 v130, s[6:7]
	s_mov_b32 m0, s44
	s_add_i32 s45, s42, 0x6000
	global_load_lds_dwordx4 v134, s[12:13]
	s_mov_b32 m0, s45
	v_mov_b32_e32 v137, 0
	global_load_lds_dwordx4 v130, s[12:13]
	v_mov_b32_e32 v133, v137
	v_mov_b32_e32 v129, v137
	v_mov_b32_e32 v135, v137
	v_mov_b32_e32 v131, v137
	s_cmp_eq_u32 s9, 1
	s_mov_b32 s46, 0
	v_lshl_add_u64 v[8:9], s[4:5], 0, v[132:133]
	v_lshl_add_u64 v[4:5], s[4:5], 0, v[128:129]
	v_lshl_add_u64 v[2:3], s[10:11], 0, v[132:133]
	v_lshl_add_u64 v[0:1], s[10:11], 0, v[128:129]
	v_lshl_add_u64 v[6:7], s[6:7], 0, v[134:135]
	s_cselect_b64 s[20:21], -1, 0
	s_cmp_lg_u32 s9, 1
	v_lshl_add_u64 v[10:11], s[6:7], 0, v[130:131]
	s_setprio 1
	s_cbranch_scc1 .LBB0_959
	s_setprio 0
	s_barrier

.LBB0_1038:
	s_andn2_b64 vcc, exec, s[2:3]
	s_cbranch_vccnz .LBB0_1080
	s_add_u32 s33, s56, 0xc200000
	s_addc_u32 s34, s57, 0
	s_add_u32 s35, s56, 0x2d00000
	s_addc_u32 s36, s57, 0
	s_ashr_i32 s1, s0, 31
	s_lshl_b64 s[8:9], s[0:1], 9
	s_ashr_i32 s4, s54, 31
	s_mul_i32 s4, s8, s4
	s_mul_hi_u32 s5, s8, s54
	s_add_i32 s10, s5, s4
	s_lshr_b64 s[4:5], s[0:1], 23
	s_mul_i32 s5, s4, s54
	s_add_i32 s10, s10, s5
	s_ashr_i32 s5, s55, 31
	s_mul_i32 s5, s8, s5
	s_mul_hi_u32 s12, s8, s55
	s_lshr_b32 s3, s18, 6
	s_add_i32 s5, s12, s5
	s_mul_i32 s4, s4, s55
	s_lshr_b32 s2, s18, 8
	v_lshlrev_b32_e32 v3, 4, v220
	v_and_b32_e32 v0, 32, v220
	v_lshlrev_b32_e32 v2, 5, v220
	s_lshl_b32 s37, s3, 10
	s_add_i32 s5, s5, s4
	s_mul_i32 s4, s8, s55
	v_bitop3_b32 v0, v3, v0, 48 bitop3:0x6c
	s_waitcnt lgkmcnt(0)
	v_and_b32_e32 v1, 64, v220
	v_and_b32_e32 v2, 0x780, v2
	s_add_u32 s26, s35, s4
	v_or3_b32 v5, v2, v1, v0
	v_and_b32_e32 v4, 0x3800, v3
	s_addc_u32 s27, s36, s5
	s_add_i32 s38, s37, 0
	v_or_b32_e32 v128, v5, v4
	v_add_u32_e32 v3, 0x2000, v3
	s_add_i32 m0, s38, 0x10000
	v_and_b32_e32 v3, 0x7800, v3
	global_load_lds_dwordx4 v128, s[26:27]
	s_add_i32 m0, s38, 0x12000
	v_or_b32_e32 v130, v5, v3
	s_add_u32 s4, s26, 0x4000
	global_load_lds_dwordx4 v130, s[26:27]
	s_addc_u32 s5, s27, 0
	s_add_i32 m0, s38, 0x14000
	s_mul_i32 s11, s8, s54
	global_load_lds_dwordx4 v128, s[4:5]
	s_add_i32 m0, s38, 0x16000
	s_add_u32 s24, s33, s11
	s_addc_u32 s25, s34, s10
	s_add_i32 s39, s38, 0x2000
	global_load_lds_dwordx4 v130, s[4:5]
	s_mov_b32 m0, s38
	s_add_u32 s4, s24, 0x4000
	global_load_lds_dwordx4 v128, s[24:25]
	s_mov_b32 m0, s39
	s_addc_u32 s5, s25, 0
	s_add_i32 s40, s38, 0x4000
	global_load_lds_dwordx4 v130, s[24:25]
	s_mov_b32 m0, s40
	s_add_i32 s41, s38, 0x6000
	global_load_lds_dwordx4 v128, s[4:5]
	s_mov_b32 m0, s41
	v_mov_b32_e32 v129, 0
	global_load_lds_dwordx4 v130, s[4:5]
	s_cmp_eq_u32 s2, 1
	s_mov_b32 s42, 0
	s_cselect_b64 s[10:11], -1, 0
	s_cmp_lg_u32 s2, 1
	v_mov_b32_e32 v131, v129
	s_setprio 1
	s_cbranch_scc1 .LBB0_1041
	s_setprio 0
	s_barrier

.LBB0_1141:
	s_andn2_b64 vcc, exec, s[2:3]
	s_cbranch_vccnz .LBB0_1199
	s_add_u32 s42, s56, 0x8200000
	s_addc_u32 s43, s57, 0
	s_waitcnt lgkmcnt(0)
	v_lshlrev_b32_e32 v1, 4, v220
	v_and_b32_e32 v0, 32, v220
	v_lshrrev_b32_e32 v2, 3, v220
	s_add_u32 s44, s56, 0x7900000
	v_bfe_u32 v14, v220, 2, 4
	v_bitop3_b32 v12, v1, v0, 48 bitop3:0x6c
	v_and_b32_e32 v13, 64, v220
	v_and_b32_e32 v16, 0x70, v2
	s_addc_u32 s45, s57, 0
	v_or_b32_e32 v0, v12, v13
	s_lshl_b32 s1, s0, 1
	v_or_b32_e32 v2, v16, v14
	v_mad_u64_u32 v[148:149], s[4:5], s1, v2, v[0:1]
	v_add_u32_e32 v1, 0x2000, v1
	v_lshrrev_b32_e32 v1, 7, v1
	v_and_b32_e32 v15, 0xf0, v1
	v_or_b32_e32 v1, v15, v14
	v_mad_u64_u32 v[150:151], s[4:5], s1, v1, v[0:1]
	s_ashr_i32 s1, s0, 31
	s_lshl_b64 s[8:9], s[0:1], 9
	s_ashr_i32 s4, s33, 31
	s_mul_i32 s4, s8, s4
	s_mul_hi_u32 s5, s8, s33
	s_add_i32 s6, s5, s4
	s_lshr_b64 s[4:5], s[0:1], 23
	s_mul_i32 s5, s4, s33
	s_add_i32 s12, s6, s5
	s_ashr_i32 s5, s40, 31
	s_mul_i32 s5, s8, s5
	s_mul_hi_u32 s6, s8, s40
	s_lshr_b32 s3, s24, 6
	s_add_i32 s5, s6, s5
	s_mul_i32 s4, s4, s40
	s_lshr_b32 s2, s24, 8
	s_lshl_b64 s[10:11], s[0:1], 8
	s_lshl_b32 s46, s3, 10
	s_add_i32 s5, s5, s4
	s_mul_i32 s4, s8, s40
	s_add_u32 s6, s44, s4
	s_addc_u32 s7, s45, s5
	s_add_i32 s47, s46, 0
	s_add_i32 m0, s47, 0x10000
	s_mul_i32 s13, s8, s33
	global_load_lds_dwordx4 v148, s[6:7]
	s_add_i32 m0, s47, 0x12000
	s_add_u32 s4, s6, s10
	global_load_lds_dwordx4 v150, s[6:7]
	s_addc_u32 s5, s7, s11
	s_add_i32 m0, s47, 0x14000
	v_mov_b32_e32 v149, 0
	global_load_lds_dwordx4 v148, s[4:5]
	s_add_i32 m0, s47, 0x16000
	s_add_u32 s38, s42, s13
	s_addc_u32 s39, s43, s12
	s_add_i32 s48, s47, 0x2000
	global_load_lds_dwordx4 v150, s[4:5]
	s_mov_b32 m0, s47
	s_add_u32 s12, s38, s10
	global_load_lds_dwordx4 v148, s[38:39]
	s_mov_b32 m0, s48
	s_addc_u32 s13, s39, s11
	s_add_i32 s49, s47, 0x4000
	global_load_lds_dwordx4 v150, s[38:39]
	s_mov_b32 m0, s49
	s_add_i32 s50, s47, 0x6000
	global_load_lds_dwordx4 v148, s[12:13]
	s_mov_b32 m0, s50
	v_mov_b32_e32 v151, v149
	global_load_lds_dwordx4 v150, s[12:13]
	s_cmp_eq_u32 s2, 1
	s_mov_b32 s51, 0
	v_lshl_add_u64 v[10:11], s[6:7], 0, v[148:149]
	v_lshl_add_u64 v[8:9], s[6:7], 0, v[150:151]
	v_lshl_add_u64 v[2:3], s[4:5], 0, v[148:149]
	v_lshl_add_u64 v[0:1], s[4:5], 0, v[150:151]
	v_lshl_add_u64 v[4:5], s[38:39], 0, v[148:149]
	s_cselect_b64 s[12:13], -1, 0
	s_cmp_lg_u32 s2, 1
	v_lshl_add_u64 v[6:7], s[38:39], 0, v[150:151]
	s_setprio 1
	s_cbranch_scc1 .LBB0_1144
	s_setprio 0
	s_barrier
